# v54 plus GEMM K-loop scalar bookkeeping moved out of the load-segment heads (after the LDS reads)
# baseline (speedup 1.0000x reference)
; #define PG8_STAGE(bufoff, gbase, voff) do { _Pragma("unroll") for (int _i = 0; _i < 2; ++_i) \
;         __builtin_amdgcn_global_load_lds((const unsigned*)((const char*)(gbase) + (voff)[_i]), (PG8_LAS unsigned*)(lds + (bufoff) + ldsw + _i * 8192), 16, 0, 0); } while (0)
; #define PG8_LDA(dst, b, h) do { _Pragma("unroll") for (int m = 0; m < 4; ++m) _Pragma("unroll") for (int k = 0; k < 2; ++k) dst[m][k] = *(const PG8_LAS bf16x8*)(lds + PG8_SA(b, h) + aoff + m * 2048 + k * 1024); } while (0)
; #define PG8_LDB(dst, b, h) do { _Pragma("unroll") for (int n = 0; n < 2; ++n) _Pragma("unroll") for (int k = 0; k < 2; ++k) dst[n][k] = *(const PG8_LAS bf16x8*)(lds + PG8_SB(b, h) + boff + n * 2048 + k * 1024); } while (0)
; #define PG8_MMA(ai, bj, At, Bt) do { __builtin_amdgcn_s_setprio(1); _Pragma("unroll") for (int m = 0; m < 4; ++m) _Pragma("unroll") for (int n = 0; n < 2; ++n) _Pragma("unroll") for (int k = 0; k < 2; ++k) \
;         acc[ai][bj][m][n] = __builtin_amdgcn_mfma_f32_16x16x32_bf16(Bt[n][k], At[m][k], acc[ai][bj][m][n], 0, 0, 0); __builtin_amdgcn_s_setprio(0); } while (0)
; #define PG8_WAIT_V(n) asm volatile("s_waitcnt vmcnt(" #n ")" ::: "memory")
; #define PG8_WAIT_L(n) asm volatile("s_waitcnt lgkmcnt(" #n ")" ::: "memory")
; #define PG8_BAR __builtin_amdgcn_s_barrier()
; #define PG8_SCHED __builtin_amdgcn_sched_barrier(0)
; __device__ __forceinline__ void gemm_phase(PG8_LAS unsigned char* lds, const Gemm g, const StaticOrder& S, const Epi& E, const int tid) {
;     ...
;         for (int t = 0; t < nt; t += 2) {
;             const bool last = (t == nt - 2);
;             const char* a1 = cA + (size_t)(t + 1) * kstep;
;             const char* a2 = last ? nA : cA + (size_t)(t + 2) * kstep; const char* b2 = last ? nB : cB + (size_t)(t + 2) * kstep;
;             const char* a3 = a2 + kstep; const char* b3 = b2 + kstep;
;             PG8_LDB(B0, 0, 0); PG8_LDB(B1, 0, 1); PG8_SCHED; PG8_LDA(At, 0, 0); PG8_STAGE(PG8_SA(1, 1), a1 + hstepA, voffA);
;             PG8_WAIT_V(8); PG8_WAIT_L(0); PG8_BAR; PG8_MMA(0, 0, At, B0); PG8_MMA(0, 1, At, B1); PG8_BAR; PG8_SCHED;
;             PG8_LDA(At, 0, 1); PG8_STAGE(PG8_SB(0, 0), b2, voffB); PG8_STAGE(PG8_SB(0, 1), b2 + hstepB, voffB); PG8_STAGE(PG8_SA(0, 0), a2, voffA);
;             PG8_WAIT_V(8); PG8_WAIT_L(0); PG8_BAR; PG8_MMA(1, 0, At, B0); PG8_MMA(1, 1, At, B1); PG8_BAR; PG8_SCHED;
.LBB0_88:
	v_add_u32_e32 v160, 0x10000, v186
	v_add_u32_e32 v189, 0x14000, v186
	ds_read_b128 v[136:139], v160
	ds_read_b128 v[140:143], v160 offset:1024
	ds_read_b128 v[156:159], v160 offset:2048
	ds_read_b128 v[160:163], v160 offset:3072
	ds_read_b128 v[164:167], v189
	ds_read_b128 v[168:171], v189 offset:1024
	ds_read_b128 v[172:175], v189 offset:2048
	ds_read_b128 v[190:193], v189 offset:3072
	v_lshl_add_u64 v[210:211], s[10:11], 0, v[152:153]
	s_add_i32 m0, s3, 0xc000
	ds_read_b128 v[194:197], v188
	ds_read_b128 v[198:201], v188 offset:1024
	ds_read_b128 v[202:205], v188 offset:2048
	ds_read_b128 v[206:209], v188 offset:3072
	ds_read_b128 v[224:227], v188 offset:4096
	ds_read_b128 v[228:231], v188 offset:5120
	ds_read_b128 v[232:235], v188 offset:6144
	ds_read_b128 v[236:239], v188 offset:7168
	global_load_lds_dwordx4 v[210:211], off
	v_lshl_add_u64 v[210:211], s[10:11], 0, v[154:155]
	s_add_i32 m0, s3, 0xe000
	s_nop 0
	global_load_lds_dwordx4 v[210:211], off
	s_add_i32 s49, s44, 2
	s_add_u32 s68, s10, 0x80
	s_addc_u32 s45, s11, 0
	s_add_i32 s78, 0, 0x10000
	s_cmp_eq_u32 s15, s44
	s_cselect_b32 s45, s5, s45
	s_cselect_b32 s44, s4, s68
	s_cselect_b32 s69, s39, s48
	s_cselect_b32 s68, s38, s47
	s_add_i32 s79, 0, 0x14000
	s_waitcnt vmcnt(8)
	s_waitcnt lgkmcnt(0)
	s_barrier
	s_setprio 1
	s_waitcnt lgkmcnt(0)
	v_mfma_f32_16x16x32_bf16 v[132:135], v[136:139], v[194:197], v[132:135]
	v_mfma_f32_16x16x32_bf16 v[128:131], v[156:159], v[194:197], v[128:131]
	v_mfma_f32_16x16x32_bf16 v[116:119], v[136:139], v[202:205], v[116:119]
	v_mfma_f32_16x16x32_bf16 v[106:109], v[156:159], v[202:205], v[106:109]
	v_mfma_f32_16x16x32_bf16 v[94:97], v[136:139], v[224:227], v[94:97]
	v_mfma_f32_16x16x32_bf16 v[90:93], v[156:159], v[224:227], v[90:93]
	v_mfma_f32_16x16x32_bf16 v[78:81], v[136:139], v[232:235], v[78:81]
	v_mfma_f32_16x16x32_bf16 v[74:77], v[156:159], v[232:235], v[74:77]
	v_mfma_f32_16x16x32_bf16 v[132:135], v[140:143], v[198:201], v[132:135]
	v_mfma_f32_16x16x32_bf16 v[128:131], v[160:163], v[198:201], v[128:131]
	v_mfma_f32_16x16x32_bf16 v[116:119], v[140:143], v[206:209], v[116:119]
	v_mfma_f32_16x16x32_bf16 v[106:109], v[160:163], v[206:209], v[106:109]
	v_mfma_f32_16x16x32_bf16 v[94:97], v[140:143], v[228:231], v[94:97]
	v_mfma_f32_16x16x32_bf16 v[90:93], v[160:163], v[228:231], v[90:93]
	v_mfma_f32_16x16x32_bf16 v[78:81], v[140:143], v[236:239], v[78:81]
	v_mfma_f32_16x16x32_bf16 v[74:77], v[160:163], v[236:239], v[74:77]
	s_setprio 0
	s_setprio 1
	v_mfma_f32_16x16x32_bf16 v[124:127], v[164:167], v[194:197], v[124:127]
	v_mfma_f32_16x16x32_bf16 v[120:123], v[172:175], v[194:197], v[120:123]
	v_mfma_f32_16x16x32_bf16 v[102:105], v[164:167], v[202:205], v[102:105]
	v_mfma_f32_16x16x32_bf16 v[98:101], v[172:175], v[202:205], v[98:101]
	v_mfma_f32_16x16x32_bf16 v[86:89], v[164:167], v[224:227], v[86:89]
	v_mfma_f32_16x16x32_bf16 v[82:85], v[172:175], v[224:227], v[82:85]
	v_mfma_f32_16x16x32_bf16 v[70:73], v[164:167], v[232:235], v[70:73]
	v_mfma_f32_16x16x32_bf16 v[66:69], v[172:175], v[232:235], v[66:69]
	v_mfma_f32_16x16x32_bf16 v[124:127], v[168:171], v[198:201], v[124:127]
	v_mfma_f32_16x16x32_bf16 v[120:123], v[190:193], v[198:201], v[120:123]
	v_mfma_f32_16x16x32_bf16 v[102:105], v[168:171], v[206:209], v[102:105]
	v_mfma_f32_16x16x32_bf16 v[98:101], v[190:193], v[206:209], v[98:101]
	v_mfma_f32_16x16x32_bf16 v[86:89], v[168:171], v[228:231], v[86:89]
	v_mfma_f32_16x16x32_bf16 v[82:85], v[190:193], v[228:231], v[82:85]
	v_mfma_f32_16x16x32_bf16 v[70:73], v[168:171], v[236:239], v[70:73]
	v_mfma_f32_16x16x32_bf16 v[66:69], v[190:193], v[236:239], v[66:69]
	s_setprio 0
	s_barrier
	s_add_i32 s78, s78, s31
	v_lshl_add_u64 v[210:211], s[68:69], 0, v[146:147]
	s_mov_b32 m0, s78
	ds_read_b128 v[194:197], v188 offset:16384
	ds_read_b128 v[198:201], v188 offset:17408
	ds_read_b128 v[202:205], v188 offset:18432
	ds_read_b128 v[206:209], v188 offset:19456
	ds_read_b128 v[224:227], v188 offset:20480
	ds_read_b128 v[228:231], v188 offset:21504
	ds_read_b128 v[232:235], v188 offset:22528
	ds_read_b128 v[236:239], v188 offset:23552
	global_load_lds_dwordx4 v[210:211], off
	s_add_i32 m0, s78, 0x2000
	v_lshl_add_u64 v[240:241], s[68:69], 0, v[150:151]
	s_add_u32 s68, s68, s34
	s_addc_u32 s69, s69, 0
	s_add_i32 s78, s79, s31
	global_load_lds_dwordx4 v[240:241], off
	v_lshl_add_u64 v[242:243], s[68:69], 0, v[146:147]
	s_mov_b32 m0, s78
	v_lshl_add_u64 v[244:245], s[68:69], 0, v[150:151]
	global_load_lds_dwordx4 v[242:243], off
	s_add_i32 m0, s78, 0x2000
	v_lshl_add_u64 v[246:247], s[44:45], 0, v[144:145]
	global_load_lds_dwordx4 v[244:245], off
	s_mov_b32 m0, s3
	v_lshl_add_u64 v[248:249], s[44:45], 0, v[148:149]
	global_load_lds_dwordx4 v[246:247], off
	s_mov_b32 m0, s17
	s_nop 0
	global_load_lds_dwordx4 v[248:249], off
	s_waitcnt vmcnt(8)
	s_waitcnt lgkmcnt(0)
	s_barrier
; #define PG8_STAGE(bufoff, gbase, voff) do { _Pragma("unroll") for (int _i = 0; _i < 2; ++_i) \
;         __builtin_amdgcn_global_load_lds((const unsigned*)((const char*)(gbase) + (voff)[_i]), (PG8_LAS unsigned*)(lds + (bufoff) + ldsw + _i * 8192), 16, 0, 0); } while (0)
; #define PG8_LDA(dst, b, h) do { _Pragma("unroll") for (int m = 0; m < 4; ++m) _Pragma("unroll") for (int k = 0; k < 2; ++k) dst[m][k] = *(const PG8_LAS bf16x8*)(lds + PG8_SA(b, h) + aoff + m * 2048 + k * 1024); } while (0)
; #define PG8_LDB(dst, b, h) do { _Pragma("unroll") for (int n = 0; n < 2; ++n) _Pragma("unroll") for (int k = 0; k < 2; ++k) dst[n][k] = *(const PG8_LAS bf16x8*)(lds + PG8_SB(b, h) + boff + n * 2048 + k * 1024); } while (0)
; #define PG8_MMA(ai, bj, At, Bt) do { __builtin_amdgcn_s_setprio(1); _Pragma("unroll") for (int m = 0; m < 4; ++m) _Pragma("unroll") for (int n = 0; n < 2; ++n) _Pragma("unroll") for (int k = 0; k < 2; ++k) \
;         acc[ai][bj][m][n] = __builtin_amdgcn_mfma_f32_16x16x32_bf16(Bt[n][k], At[m][k], acc[ai][bj][m][n], 0, 0, 0); __builtin_amdgcn_s_setprio(0); } while (0)
; #define PG8_WAIT_V(n) asm volatile("s_waitcnt vmcnt(" #n ")" ::: "memory")
; #define PG8_WAIT_L(n) asm volatile("s_waitcnt lgkmcnt(" #n ")" ::: "memory")
; #define PG8_BAR __builtin_amdgcn_s_barrier()
; #define PG8_SCHED __builtin_amdgcn_sched_barrier(0)
; __device__ __forceinline__ void gemm_phase(PG8_LAS unsigned char* lds, const Gemm g, const StaticOrder& S, const Epi& E, const int tid) {
;     ...
;             PG8_WAIT_V(8); PG8_WAIT_L(0); PG8_BAR; PG8_MMA(1, 0, At, B0); PG8_MMA(1, 1, At, B1); PG8_BAR; PG8_SCHED;
;             PG8_LDB(B0, 1, 0); PG8_LDB(B1, 1, 1); PG8_SCHED; PG8_LDA(At, 1, 0); PG8_STAGE(PG8_SA(0, 1), a2 + hstepA, voffA);
;             PG8_WAIT_V(8); PG8_WAIT_L(0); PG8_BAR; PG8_MMA(0, 0, At, B0); PG8_MMA(0, 1, At, B1); PG8_BAR; PG8_SCHED;
	s_setprio 1
	s_waitcnt lgkmcnt(0)
	v_mfma_f32_16x16x32_bf16 v[62:65], v[136:139], v[194:197], v[62:65]
	v_mfma_f32_16x16x32_bf16 v[58:61], v[156:159], v[194:197], v[58:61]
	v_mfma_f32_16x16x32_bf16 v[46:49], v[136:139], v[202:205], v[46:49]
	v_mfma_f32_16x16x32_bf16 v[42:45], v[156:159], v[202:205], v[42:45]
	v_mfma_f32_16x16x32_bf16 v[30:33], v[136:139], v[224:227], v[30:33]
	v_mfma_f32_16x16x32_bf16 v[26:29], v[156:159], v[224:227], v[26:29]
	v_mfma_f32_16x16x32_bf16 v[14:17], v[136:139], v[232:235], v[14:17]
	v_mfma_f32_16x16x32_bf16 v[10:13], v[156:159], v[232:235], v[10:13]
	v_mfma_f32_16x16x32_bf16 v[62:65], v[140:143], v[198:201], v[62:65]
	v_mfma_f32_16x16x32_bf16 v[58:61], v[160:163], v[198:201], v[58:61]
	v_mfma_f32_16x16x32_bf16 v[46:49], v[140:143], v[206:209], v[46:49]
	v_mfma_f32_16x16x32_bf16 v[42:45], v[160:163], v[206:209], v[42:45]
	v_mfma_f32_16x16x32_bf16 v[30:33], v[140:143], v[228:231], v[30:33]
	v_mfma_f32_16x16x32_bf16 v[26:29], v[160:163], v[228:231], v[26:29]
	v_mfma_f32_16x16x32_bf16 v[14:17], v[140:143], v[236:239], v[14:17]
	v_mfma_f32_16x16x32_bf16 v[10:13], v[160:163], v[236:239], v[10:13]
	s_setprio 0
	s_setprio 1
	v_mfma_f32_16x16x32_bf16 v[54:57], v[164:167], v[194:197], v[54:57]
	v_mfma_f32_16x16x32_bf16 v[50:53], v[172:175], v[194:197], v[50:53]
	v_mfma_f32_16x16x32_bf16 v[38:41], v[164:167], v[202:205], v[38:41]
	v_mfma_f32_16x16x32_bf16 v[34:37], v[172:175], v[202:205], v[34:37]
	v_mfma_f32_16x16x32_bf16 v[22:25], v[164:167], v[224:227], v[22:25]
	v_mfma_f32_16x16x32_bf16 v[18:21], v[172:175], v[224:227], v[18:21]
	v_mfma_f32_16x16x32_bf16 v[6:9], v[164:167], v[232:235], v[6:9]
	v_mfma_f32_16x16x32_bf16 v[2:5], v[172:175], v[232:235], v[2:5]
	v_mfma_f32_16x16x32_bf16 v[54:57], v[168:171], v[198:201], v[54:57]
	v_mfma_f32_16x16x32_bf16 v[50:53], v[190:193], v[198:201], v[50:53]
	v_mfma_f32_16x16x32_bf16 v[38:41], v[168:171], v[206:209], v[38:41]
	v_mfma_f32_16x16x32_bf16 v[34:37], v[190:193], v[206:209], v[34:37]
	v_mfma_f32_16x16x32_bf16 v[22:25], v[168:171], v[228:231], v[22:25]
	v_mfma_f32_16x16x32_bf16 v[18:21], v[190:193], v[228:231], v[18:21]
	v_mfma_f32_16x16x32_bf16 v[6:9], v[168:171], v[236:239], v[6:9]
	v_mfma_f32_16x16x32_bf16 v[2:5], v[190:193], v[236:239], v[2:5]
	s_setprio 0
	s_barrier
	v_add_u32_e32 v160, 0x18000, v186
	v_add_u32_e32 v189, 0x1c000, v186
	ds_read_b128 v[136:139], v160
	ds_read_b128 v[140:143], v160 offset:1024
	ds_read_b128 v[156:159], v160 offset:2048
	ds_read_b128 v[160:163], v160 offset:3072
	ds_read_b128 v[164:167], v189
	ds_read_b128 v[168:171], v189 offset:1024
	ds_read_b128 v[172:175], v189 offset:2048
	ds_read_b128 v[190:193], v189 offset:3072
	s_add_i32 s68, 0, 0x18000
	s_add_i32 s69, 0, 0x1c000
	s_add_u32 s44, s44, s0
	s_addc_u32 s45, s45, 0
	s_mov_b32 m0, s58
	v_lshl_add_u64 v[250:251], s[44:45], 0, v[144:145]
	ds_read_b128 v[194:197], v188 offset:32768
	ds_read_b128 v[198:201], v188 offset:33792
	ds_read_b128 v[202:205], v188 offset:34816
	ds_read_b128 v[206:209], v188 offset:35840
	ds_read_b128 v[224:227], v188 offset:36864
	ds_read_b128 v[228:231], v188 offset:37888
	ds_read_b128 v[232:235], v188 offset:38912
	ds_read_b128 v[236:239], v188 offset:39936
	global_load_lds_dwordx4 v[250:251], off
	v_lshl_add_u64 v[250:251], s[44:45], 0, v[148:149]
	s_mov_b32 m0, s59
	s_nop 0
	global_load_lds_dwordx4 v[250:251], off
	s_waitcnt vmcnt(8)
	s_waitcnt lgkmcnt(0)
	s_barrier
	s_setprio 1
	s_waitcnt lgkmcnt(0)
	v_mfma_f32_16x16x32_bf16 v[132:135], v[136:139], v[194:197], v[132:135]
	v_mfma_f32_16x16x32_bf16 v[128:131], v[156:159], v[194:197], v[128:131]
	v_mfma_f32_16x16x32_bf16 v[116:119], v[136:139], v[202:205], v[116:119]
	v_mfma_f32_16x16x32_bf16 v[106:109], v[156:159], v[202:205], v[106:109]
	v_mfma_f32_16x16x32_bf16 v[94:97], v[136:139], v[224:227], v[94:97]
	v_mfma_f32_16x16x32_bf16 v[90:93], v[156:159], v[224:227], v[90:93]
	v_mfma_f32_16x16x32_bf16 v[78:81], v[136:139], v[232:235], v[78:81]
	v_mfma_f32_16x16x32_bf16 v[74:77], v[156:159], v[232:235], v[74:77]
	v_mfma_f32_16x16x32_bf16 v[132:135], v[140:143], v[198:201], v[132:135]
	v_mfma_f32_16x16x32_bf16 v[128:131], v[160:163], v[198:201], v[128:131]
	v_mfma_f32_16x16x32_bf16 v[116:119], v[140:143], v[206:209], v[116:119]
	v_mfma_f32_16x16x32_bf16 v[106:109], v[160:163], v[206:209], v[106:109]
	v_mfma_f32_16x16x32_bf16 v[94:97], v[140:143], v[228:231], v[94:97]
	v_mfma_f32_16x16x32_bf16 v[90:93], v[160:163], v[228:231], v[90:93]
	v_mfma_f32_16x16x32_bf16 v[78:81], v[140:143], v[236:239], v[78:81]
	v_mfma_f32_16x16x32_bf16 v[74:77], v[160:163], v[236:239], v[74:77]
	s_setprio 0
	s_setprio 1
	v_mfma_f32_16x16x32_bf16 v[124:127], v[164:167], v[194:197], v[124:127]
	v_mfma_f32_16x16x32_bf16 v[120:123], v[172:175], v[194:197], v[120:123]
	v_mfma_f32_16x16x32_bf16 v[102:105], v[164:167], v[202:205], v[102:105]
	v_mfma_f32_16x16x32_bf16 v[98:101], v[172:175], v[202:205], v[98:101]
	v_mfma_f32_16x16x32_bf16 v[86:89], v[164:167], v[224:227], v[86:89]
	v_mfma_f32_16x16x32_bf16 v[82:85], v[172:175], v[224:227], v[82:85]
	v_mfma_f32_16x16x32_bf16 v[70:73], v[164:167], v[232:235], v[70:73]
	v_mfma_f32_16x16x32_bf16 v[66:69], v[172:175], v[232:235], v[66:69]
	v_mfma_f32_16x16x32_bf16 v[124:127], v[168:171], v[198:201], v[124:127]
	v_mfma_f32_16x16x32_bf16 v[120:123], v[190:193], v[198:201], v[120:123]
	v_mfma_f32_16x16x32_bf16 v[102:105], v[168:171], v[206:209], v[102:105]
	v_mfma_f32_16x16x32_bf16 v[98:101], v[190:193], v[206:209], v[98:101]
	v_mfma_f32_16x16x32_bf16 v[86:89], v[168:171], v[228:231], v[86:89]
	v_mfma_f32_16x16x32_bf16 v[82:85], v[190:193], v[228:231], v[82:85]
	v_mfma_f32_16x16x32_bf16 v[70:73], v[168:171], v[236:239], v[70:73]
	v_mfma_f32_16x16x32_bf16 v[66:69], v[190:193], v[236:239], v[66:69]
	s_setprio 0
	s_barrier
; #define PG8_STAGE(bufoff, gbase, voff) do { _Pragma("unroll") for (int _i = 0; _i < 2; ++_i) \
;         __builtin_amdgcn_global_load_lds((const unsigned*)((const char*)(gbase) + (voff)[_i]), (PG8_LAS unsigned*)(lds + (bufoff) + ldsw + _i * 8192), 16, 0, 0); } while (0)
; #define PG8_LDA(dst, b, h) do { _Pragma("unroll") for (int m = 0; m < 4; ++m) _Pragma("unroll") for (int k = 0; k < 2; ++k) dst[m][k] = *(const PG8_LAS bf16x8*)(lds + PG8_SA(b, h) + aoff + m * 2048 + k * 1024); } while (0)
; #define PG8_MMA(ai, bj, At, Bt) do { __builtin_amdgcn_s_setprio(1); _Pragma("unroll") for (int m = 0; m < 4; ++m) _Pragma("unroll") for (int n = 0; n < 2; ++n) _Pragma("unroll") for (int k = 0; k < 2; ++k) \
;         acc[ai][bj][m][n] = __builtin_amdgcn_mfma_f32_16x16x32_bf16(Bt[n][k], At[m][k], acc[ai][bj][m][n], 0, 0, 0); __builtin_amdgcn_s_setprio(0); } while (0)
; #define PG8_WAIT_V(n) asm volatile("s_waitcnt vmcnt(" #n ")" ::: "memory")
; #define PG8_WAIT_L(n) asm volatile("s_waitcnt lgkmcnt(" #n ")" ::: "memory")
; #define PG8_BAR __builtin_amdgcn_s_barrier()
; #define PG8_SCHED __builtin_amdgcn_sched_barrier(0)
; __device__ __forceinline__ void gemm_phase(PG8_LAS unsigned char* lds, const Gemm g, const StaticOrder& S, const Epi& E, const int tid) {
;     ...
;             PG8_LDA(At, 1, 1); PG8_STAGE(PG8_SB(1, 0), b3, voffB); PG8_STAGE(PG8_SB(1, 1), b3 + hstepB, voffB); PG8_STAGE(PG8_SA(1, 0), a3, voffA);
;             PG8_WAIT_V(8); PG8_WAIT_L(0); PG8_BAR; PG8_MMA(1, 0, At, B0); PG8_MMA(1, 1, At, B1); PG8_BAR; PG8_SCHED;
;         }
	s_add_i32 s44, s68, s31
	v_lshl_add_u64 v[210:211], v[210:211], 0, s[36:37]
	s_mov_b32 m0, s44
	ds_read_b128 v[194:197], v188 offset:49152
	ds_read_b128 v[198:201], v188 offset:50176
	ds_read_b128 v[202:205], v188 offset:51200
	ds_read_b128 v[206:209], v188 offset:52224
	ds_read_b128 v[224:227], v188 offset:53248
	ds_read_b128 v[228:231], v188 offset:54272
	ds_read_b128 v[232:235], v188 offset:55296
	ds_read_b128 v[236:239], v188 offset:56320
	global_load_lds_dwordx4 v[210:211], off
	v_lshl_add_u64 v[210:211], v[240:241], 0, s[36:37]
	s_add_i32 m0, s44, 0x2000
	s_add_i32 s44, s69, s31
	global_load_lds_dwordx4 v[210:211], off
	v_lshl_add_u64 v[210:211], v[242:243], 0, s[36:37]
	s_mov_b32 m0, s44
	s_nop 0
	global_load_lds_dwordx4 v[210:211], off
	v_lshl_add_u64 v[210:211], v[244:245], 0, s[36:37]
	s_add_i32 m0, s44, 0x2000
	s_nop 0
	global_load_lds_dwordx4 v[210:211], off
	v_lshl_add_u64 v[210:211], v[246:247], 0, s[36:37]
	s_mov_b32 m0, s12
	s_nop 0
	global_load_lds_dwordx4 v[210:211], off
	v_lshl_add_u64 v[210:211], v[248:249], 0, s[36:37]
	s_mov_b32 m0, s13
	s_nop 0
	global_load_lds_dwordx4 v[210:211], off
	s_waitcnt vmcnt(8)
	s_waitcnt lgkmcnt(0)
	s_barrier
	s_setprio 1
	s_waitcnt lgkmcnt(0)
	v_mfma_f32_16x16x32_bf16 v[62:65], v[136:139], v[194:197], v[62:65]
	v_mfma_f32_16x16x32_bf16 v[58:61], v[156:159], v[194:197], v[58:61]
	v_mfma_f32_16x16x32_bf16 v[46:49], v[136:139], v[202:205], v[46:49]
	v_mfma_f32_16x16x32_bf16 v[42:45], v[156:159], v[202:205], v[42:45]
	v_mfma_f32_16x16x32_bf16 v[30:33], v[136:139], v[224:227], v[30:33]
	v_mfma_f32_16x16x32_bf16 v[26:29], v[156:159], v[224:227], v[26:29]
	v_mfma_f32_16x16x32_bf16 v[14:17], v[136:139], v[232:235], v[14:17]
	v_mfma_f32_16x16x32_bf16 v[10:13], v[156:159], v[232:235], v[10:13]
	v_mfma_f32_16x16x32_bf16 v[62:65], v[140:143], v[198:201], v[62:65]
	v_mfma_f32_16x16x32_bf16 v[58:61], v[160:163], v[198:201], v[58:61]
	v_mfma_f32_16x16x32_bf16 v[46:49], v[140:143], v[206:209], v[46:49]
	v_mfma_f32_16x16x32_bf16 v[42:45], v[160:163], v[206:209], v[42:45]
	v_mfma_f32_16x16x32_bf16 v[30:33], v[140:143], v[228:231], v[30:33]
	v_mfma_f32_16x16x32_bf16 v[26:29], v[160:163], v[228:231], v[26:29]
	v_mfma_f32_16x16x32_bf16 v[14:17], v[140:143], v[236:239], v[14:17]
	v_mfma_f32_16x16x32_bf16 v[10:13], v[160:163], v[236:239], v[10:13]
	s_setprio 0
	s_setprio 1
	v_mfma_f32_16x16x32_bf16 v[54:57], v[164:167], v[194:197], v[54:57]
	v_mfma_f32_16x16x32_bf16 v[50:53], v[172:175], v[194:197], v[50:53]
	v_mfma_f32_16x16x32_bf16 v[38:41], v[164:167], v[202:205], v[38:41]
	v_mfma_f32_16x16x32_bf16 v[34:37], v[172:175], v[202:205], v[34:37]
	v_mfma_f32_16x16x32_bf16 v[22:25], v[164:167], v[224:227], v[22:25]
	v_mfma_f32_16x16x32_bf16 v[18:21], v[172:175], v[224:227], v[18:21]
	v_mfma_f32_16x16x32_bf16 v[6:9], v[164:167], v[232:235], v[6:9]
	v_mfma_f32_16x16x32_bf16 v[2:5], v[172:175], v[232:235], v[2:5]
	v_mfma_f32_16x16x32_bf16 v[54:57], v[168:171], v[198:201], v[54:57]
	v_mfma_f32_16x16x32_bf16 v[50:53], v[190:193], v[198:201], v[50:53]
	v_mfma_f32_16x16x32_bf16 v[38:41], v[168:171], v[206:209], v[38:41]
	v_mfma_f32_16x16x32_bf16 v[34:37], v[190:193], v[206:209], v[34:37]
	v_mfma_f32_16x16x32_bf16 v[22:25], v[168:171], v[228:231], v[22:25]
	v_mfma_f32_16x16x32_bf16 v[18:21], v[190:193], v[228:231], v[18:21]
	v_mfma_f32_16x16x32_bf16 v[6:9], v[168:171], v[236:239], v[6:9]
	v_mfma_f32_16x16x32_bf16 v[2:5], v[190:193], v[236:239], v[2:5]
	s_setprio 0
	s_barrier
	s_add_u32 s10, s10, 0x100
	s_addc_u32 s11, s11, 0
	s_add_u32 s47, s47, 0x100
	s_addc_u32 s48, s48, 0
	s_cmp_ge_u32 s49, s14
	s_mov_b32 s44, s49
	s_cbranch_scc0 .LBB0_88
	s_and_b64 vcc, exec, s[72:73]
	s_cbranch_vccz .LBB0_91
	s_barrier
